# indexer rewritten by hand: key tiles staged once per workgroup in LDS via LDS-DMA (static LDS +16KiB), K=32 f16 MFMA for head sum, prefix-skip radix select, collective compaction; plus sparse rewrite
# speedup vs baseline: 1.3090x; 1.0496x over previous
; #define LAS __attribute__((address_space(3)))
; __device__ __forceinline__ void indexer_unit(const bf16_t* IQ, const bf16_t* IK, const float* IW, unsigned short* SEL, LAS unsigned char* wlds, int t0, int lane) {
;     const int n16 = lane & 15, slab = lane >> 4;
;     bf16x8 a0[NQI], a1[NQI]; h4_t wa[NQI][4]; int cnt[NQI]; float tau[NQI];
; #pragma unroll
;     for (int q = 0; q < NQI; ++q) { const size_t t = (size_t)(t0 + q);
;         a0[q] = *(const bf16x8*)(IQ + t * 1024 + n16 * 64 + slab * 8); a1[q] = *(const bf16x8*)(IQ + t * 1024 + n16 * 64 + 32 + slab * 8);
;         const f32x4 wv = *(const f32x4*)(IW + t * 16 + slab * 4); const h4_t wh = {(_Float16)wv[0], (_Float16)wv[1], (_Float16)wv[2], (_Float16)wv[3]};
;         const h4_t hz = {(_Float16)0, (_Float16)0, (_Float16)0, (_Float16)0};
; #pragma unroll
;         for (int g = 0; g < 4; ++g) wa[q][g] = (n16 == 4 * g) ? wh : hz;
;         cnt[q] = 0; tau[q] = -INFINITY; }
;     const int nkb = t0 / 64 + 1;
; #pragma unroll
;     for (int q = 0; q < NQI; ++q) asm volatile("" :: "v"(a0[q]), "v"(a1[q]), "v"(wa[q][0]), "v"(wa[q][1]), "v"(wa[q][2]), "v"(wa[q][3]));
;     bf16x8 fa[8], fb[8];
; #pragma unroll
;     for (int i = 0; i < 8; ++i) { fa[i] = (bf16x8){0, 0, 0, 0, 0, 0, 0, 0}; fb[i] = fa[i]; }
;     idx_load(fa, IK, 0, n16, slab);
; #pragma unroll 1
;     for (int kb = 0; kb < nkb; kb += 2) {
;         idx_load(fb, IK, min(kb + 1, nkb - 1), n16, slab);
; __global__ void __launch_bounds__(NTHREADS, 2) mega(Args a) {
;     ...
;                 for (int rep = 0; rep < REP_IDX; ++rep) for (int pr = gw; pr < SEQ / NQI / 2; pr += NGW) {
;                     indexer_unit(IQ, IK, IW, SEL, lds + wave * 16384, (SEQ / NQI - 1 - pr) * NQI, lane); indexer_unit(IQ, IK, IW, SEL, lds + wave * 16384, pr * NQI, lane); }
.LBB0_220:
	s_cmpk_gt_i32 s12, 0x7ff
	s_barrier
	s_cbranch_scc1 .LBB0_1003
	v_readlane_b32 s0, v250, 18
	v_readlane_b32 s1, v251, 0
	s_nop 3
	s_lshl_b32 s82, s0, 14
	s_lshl_b32 s1, s1, 3
	v_writelane_b32 v249, s1, 0
	s_add_u32 s38, s90, 0x26300000
	s_addc_u32 s39, s91, 0
	s_add_u32 s40, s90, 0x28300000
	s_addc_u32 s41, s91, 0
	s_add_u32 s42, s90, 0x28500000
	s_addc_u32 s43, s91, 0
	s_add_u32 s44, s90, 0x28600000
	s_addc_u32 s45, s91, 0
	v_and_b32_e32 v190, 15, v182
	v_lshrrev_b32_e32 v191, 4, v182
	v_lshlrev_b32_e32 v184, 7, v190
	v_lshlrev_b32_e32 v188, 4, v191
	v_lshl_add_u32 v187, v182, 2, s82
	v_lshlrev_b32_e32 v189, 1, v182
	v_and_b32_e32 v192, 7, v190
	v_xor_b32_e32 v193, v191, v192
	v_lshl_add_u32 v96, v193, 4, v184
	v_xor_b32_e32 v193, 4, v193
	v_lshl_add_u32 v97, v193, 4, v184
	v_add_u32_e32 v98, 155648, v96
	v_add_u32_e32 v99, 155648, v97
	v_add_u32_e32 v96, 147456, v96
	v_add_u32_e32 v97, 147456, v97
	v_lshl_add_u32 v184, v191, 4, v184
	v_lshrrev_b32_e32 v192, 3, v182
	v_and_b32_e32 v193, 7, v182
	v_xor_b32_e32 v193, v193, v192
	v_lshlrev_b32_e32 v192, 7, v192
	v_lshl_add_u32 v185, v193, 4, v192
	s_lshr_b32 s0, s82, 4
	v_add_u32_e32 v185, s0, v185
	v_cmp_eq_u32_e64 s[8:9], 0, v190
	v_cmp_eq_u32_e64 s[10:11], 4, v190
	v_cmp_eq_u32_e64 s[16:17], 8, v190
	v_cmp_eq_u32_e64 s[22:23], 12, v190
.Lix_pair:
	s_mov_b32 s0, 0
	v_writelane_b32 v249, s0, 1
	s_nop 1
	v_readlane_b32 s1, v249, 0
	s_lshr_b32 s0, s82, 14
	s_nop 2
	s_add_i32 s1, s1, s0
	s_sub_i32 s46, 0xfff, s1
	s_lshl_b32 s46, s46, 2
.Lix_unit:
	s_lshl_b32 s0, s46, 11
	s_add_u32 s0, s38, s0
	s_addc_u32 s1, s39, 0
	global_load_dwordx4 v[0:3], v184, s[0:1]
	global_load_dwordx4 v[16:19], v184, s[0:1] offset:64
	s_add_u32 s0, s0, 0x800
	s_addc_u32 s1, s1, 0
	global_load_dwordx4 v[4:7], v184, s[0:1]
	global_load_dwordx4 v[20:23], v184, s[0:1] offset:64
	s_add_u32 s0, s0, 0x800
	s_addc_u32 s1, s1, 0
	global_load_dwordx4 v[8:11], v184, s[0:1]
	global_load_dwordx4 v[24:27], v184, s[0:1] offset:64
	s_add_u32 s0, s0, 0x800
	s_addc_u32 s1, s1, 0
	global_load_dwordx4 v[12:15], v184, s[0:1]
	global_load_dwordx4 v[28:31], v184, s[0:1] offset:64
	s_lshl_b32 s4, s46, 6
	s_add_u32 s4, s42, s4
	s_addc_u32 s5, s43, 0
	global_load_dwordx4 v[224:227], v188, s[4:5]
	global_load_dwordx4 v[228:231], v188, s[4:5] offset:64
	global_load_dwordx4 v[232:235], v188, s[4:5] offset:128
	global_load_dwordx4 v[236:239], v188, s[4:5] offset:192
	s_mov_b32 s52, 0
	s_mov_b32 s58, 0xff800000
	s_mov_b32 s28, 0
	s_mov_b32 s53, 0
	s_mov_b32 s59, 0xff800000
	s_mov_b32 s29, 0
	s_mov_b32 s54, 0
	s_mov_b32 s60, 0xff800000
	s_mov_b32 s34, 0
	s_mov_b32 s55, 0
	s_mov_b32 s61, 0xff800000
	s_mov_b32 s35, 0
	s_mov_b32 s47, 0
	s_lshr_b32 s48, s46, 6
	s_mov_b64 s[76:77], s[40:41]
	s_mov_b32 s13, 131328
	s_mov_b32 s101, 131332
	s_mov_b32 s50, 131336
	s_barrier
	s_cmp_lg_u32 s82, 0
	s_cbranch_scc1 .Lix_noinit
	v_mov_b32_e32 v192, 131328
	v_mov_b32_e32 v193, 0
	ds_write_b32 v192, v193
	ds_write_b32 v192, v193 offset:4
	ds_write_b32 v192, v193 offset:8
	s_waitcnt lgkmcnt(0)
.Lix_noinit:
	s_lshr_b32 s0, s82, 4
	s_add_i32 m0, s0, 147456
	s_nop 0
	global_load_lds_dwordx4 v185, s[76:77]
	v_mov_b32_e32 v186, v182
	s_waitcnt vmcnt(1)
	v_cvt_pk_f16_f32 v190, v224, v225
	v_cvt_pk_f16_f32 v191, v226, v227
	s_nop 0
	v_cndmask_b32_e64 v32, 0, v190, s[8:9]
	v_cndmask_b32_e64 v33, 0, v191, s[8:9]
	v_cndmask_b32_e64 v34, 0, v190, s[10:11]
	v_cndmask_b32_e64 v35, 0, v191, s[10:11]
	v_cndmask_b32_e64 v36, 0, v190, s[16:17]
	v_cndmask_b32_e64 v37, 0, v191, s[16:17]
	v_cndmask_b32_e64 v38, 0, v190, s[22:23]
	v_cndmask_b32_e64 v39, 0, v191, s[22:23]
	v_cvt_pk_f16_f32 v190, v228, v229
	v_cvt_pk_f16_f32 v191, v230, v231
	s_nop 0
	v_cndmask_b32_e64 v40, 0, v190, s[8:9]
	v_cndmask_b32_e64 v41, 0, v191, s[8:9]
	v_cndmask_b32_e64 v42, 0, v190, s[10:11]
	v_cndmask_b32_e64 v43, 0, v191, s[10:11]
	v_cndmask_b32_e64 v44, 0, v190, s[16:17]
	v_cndmask_b32_e64 v45, 0, v191, s[16:17]
	v_cndmask_b32_e64 v46, 0, v190, s[22:23]
	v_cndmask_b32_e64 v47, 0, v191, s[22:23]
	v_cvt_pk_f16_f32 v190, v232, v233
	v_cvt_pk_f16_f32 v191, v234, v235
	s_nop 0
	v_cndmask_b32_e64 v48, 0, v190, s[8:9]
	v_cndmask_b32_e64 v49, 0, v191, s[8:9]
	v_cndmask_b32_e64 v50, 0, v190, s[10:11]
	v_cndmask_b32_e64 v51, 0, v191, s[10:11]
	v_cndmask_b32_e64 v52, 0, v190, s[16:17]
	v_cndmask_b32_e64 v53, 0, v191, s[16:17]
	v_cndmask_b32_e64 v54, 0, v190, s[22:23]
	v_cndmask_b32_e64 v55, 0, v191, s[22:23]
	v_cvt_pk_f16_f32 v190, v236, v237
	v_cvt_pk_f16_f32 v191, v238, v239
	s_nop 0
	v_cndmask_b32_e64 v56, 0, v190, s[8:9]
	v_cndmask_b32_e64 v57, 0, v191, s[8:9]
	v_cndmask_b32_e64 v58, 0, v190, s[10:11]
	v_cndmask_b32_e64 v59, 0, v191, s[10:11]
	v_cndmask_b32_e64 v60, 0, v190, s[16:17]
	v_cndmask_b32_e64 v61, 0, v191, s[16:17]
	v_cndmask_b32_e64 v62, 0, v190, s[22:23]
	v_cndmask_b32_e64 v63, 0, v191, s[22:23]
.Lix_loop:
	s_waitcnt vmcnt(0)
	s_barrier
	v_mov_b32_e32 v190, s13
	ds_read_b32 v191, v190
	ds_read_b128 v[64:67], v96 offset:0
	ds_read_b128 v[68:71], v97 offset:0
	ds_read_b128 v[72:75], v96 offset:2048
	ds_read_b128 v[76:79], v97 offset:2048
	ds_read_b128 v[80:83], v96 offset:4096
	ds_read_b128 v[84:87], v97 offset:4096
	ds_read_b128 v[88:91], v96 offset:6144
	ds_read_b128 v[92:95], v97 offset:6144
	s_cmp_ge_u32 s47, s48
	s_cbranch_scc1 .Lix_nodma0
	s_add_u32 s76, s76, 0x2000
	s_addc_u32 s77, s77, 0
	s_lshr_b32 s0, s82, 4
	s_add_i32 m0, s0, 155648
	s_nop 0
	global_load_lds_dwordx4 v185, s[76:77]
.Lix_nodma0:
	s_cmp_lg_u32 s82, 0
	s_cbranch_scc1 .Lix_noclr0
	v_mov_b32_e32 v192, s50
	v_mov_b32_e32 v193, 0
	ds_write_b32 v192, v193
; #define LAS __attribute__((address_space(3)))
; __device__ __forceinline__ int lane_prefix(unsigned long long mask) { return __builtin_amdgcn_mbcnt_hi((unsigned)(mask >> 32), __builtin_amdgcn_mbcnt_lo((unsigned)mask, 0)); }
; __device__ __forceinline__ float idx_score(const bf16x8 (&f)[8], const bf16x8 a0, const bf16x8 a1, const h4_t (&wa)[4]) {
;     f32x4 s = {0.f, 0.f, 0.f, 0.f}; const h2_t z = {(_Float16)0, (_Float16)0};
; #pragma unroll
;     for (int g = 0; g < 4; ++g) {
;         f32x4 acc = {0.f, 0.f, 0.f, 0.f};
;         acc = __builtin_amdgcn_mfma_f32_16x16x32_bf16(a0, f[2 * g], acc, 0, 0, 0);
;         acc = __builtin_amdgcn_mfma_f32_16x16x32_bf16(a1, f[2 * g + 1], acc, 0, 0, 0);
;         h2_t lo = {(_Float16)acc[0], (_Float16)acc[1]}, hi = {(_Float16)acc[2], (_Float16)acc[3]};
;         lo = __builtin_elementwise_max(lo, z); hi = __builtin_elementwise_max(hi, z);
;         const h4_t bb = {lo[0], lo[1], hi[0], hi[1]};
;         s = __builtin_amdgcn_mfma_f32_16x16x16f16(wa[g], bb, s, 0, 0, 0);
;     }
;     return s[0];
; }
; __device__ __forceinline__ void idx_append(float score, LAS float* bs, LAS unsigned* bi, int& cnt, float& tau, int kb, int t, int lane) {
;     const int kidx = kb * 64 + lane;
;     const bool valid = (kidx <= t) && (score > tau);
;     const unsigned long long vm = __ballot(valid); const int pos = cnt + lane_prefix(vm);
;     if (valid) { bs[pos] = score; bi[pos] = (unsigned)kidx; }
;     cnt += __popcll(vm);
;     __builtin_amdgcn_wave_barrier();
;     if (cnt > ICAP - 64) idx_compact(bs, bi, cnt, tau, lane);
.Lix_noclr0:
	s_waitcnt lgkmcnt(0)
	v_readfirstlane_b32 s49, v191
	s_nop 3
	s_cmp_eq_u32 s49, 0
	s_cbranch_scc1 .Lix_nocomp0
	s_bitcmp1_b32 s49, 0
	s_cbranch_scc0 .Lix_ncq0_0
	s_cmpk_lt_i32 s52, 0x141
	s_cbranch_scc1 .Lix_ncq0_0
	s_add_i32 s79, s82, 0
	s_mov_b32 s80, s52
	s_mov_b32 s56, s28
	s_movk_i32 s19, 288
	s_mov_b32 s78, 0
	s_branch .Lix_compact
.Lix_ret0:
	s_mov_b32 s58, s81
	s_mov_b32 s28, s56
	s_mov_b32 s52, s80
.Lix_ncq0_0:
	s_bitcmp1_b32 s49, 1
	s_cbranch_scc0 .Lix_ncq0_1
	s_cmpk_lt_i32 s53, 0x141
	s_cbranch_scc1 .Lix_ncq0_1
	s_add_i32 s79, s82, 4096
	s_mov_b32 s80, s53
	s_mov_b32 s56, s29
	s_movk_i32 s19, 288
	s_mov_b32 s78, 1
	s_branch .Lix_compact
.Lix_ret1:
	s_mov_b32 s59, s81
	s_mov_b32 s29, s56
	s_mov_b32 s53, s80
.Lix_ncq0_1:
	s_bitcmp1_b32 s49, 2
	s_cbranch_scc0 .Lix_ncq0_2
	s_cmpk_lt_i32 s54, 0x141
	s_cbranch_scc1 .Lix_ncq0_2
	s_add_i32 s79, s82, 8192
	s_mov_b32 s80, s54
	s_mov_b32 s56, s34
	s_movk_i32 s19, 288
	s_mov_b32 s78, 2
	s_branch .Lix_compact
.Lix_ret2:
	s_mov_b32 s60, s81
	s_mov_b32 s34, s56
	s_mov_b32 s54, s80
.Lix_ncq0_2:
	s_bitcmp1_b32 s49, 3
	s_cbranch_scc0 .Lix_ncq0_3
	s_cmpk_lt_i32 s55, 0x141
	s_cbranch_scc1 .Lix_ncq0_3
	s_add_i32 s79, s82, 12288
	s_mov_b32 s80, s55
	s_mov_b32 s56, s35
	s_movk_i32 s19, 288
	s_mov_b32 s78, 3
	s_branch .Lix_compact
.Lix_ret3:
	s_mov_b32 s61, s81
	s_mov_b32 s35, s56
	s_mov_b32 s55, s80
.Lix_ncq0_3:
.Lix_nocomp0:
	v_mfma_f32_16x16x32_bf16 v[144:147], v[0:3], v[64:67], 0
	v_mfma_f32_16x16x32_bf16 v[144:147], v[16:19], v[68:71], v[144:147]
	v_mfma_f32_16x16x32_bf16 v[148:151], v[0:3], v[72:75], 0
	v_mfma_f32_16x16x32_bf16 v[148:151], v[16:19], v[76:79], v[148:151]
	v_mfma_f32_16x16x32_bf16 v[152:155], v[0:3], v[80:83], 0
	v_mfma_f32_16x16x32_bf16 v[152:155], v[16:19], v[84:87], v[152:155]
	v_mfma_f32_16x16x32_bf16 v[156:159], v[0:3], v[88:91], 0
	s_nop 2
	v_cvt_pk_f16_f32 v196, v144, v145
	v_cvt_pk_f16_f32 v197, v146, v147
	v_mfma_f32_16x16x32_bf16 v[156:159], v[16:19], v[92:95], v[156:159]
	v_pk_max_f16 v196, v196, 0
	v_pk_max_f16 v197, v197, 0
	v_mfma_f32_16x16x32_bf16 v[144:147], v[4:7], v[64:67], 0
	v_cvt_pk_f16_f32 v198, v148, v149
	v_cvt_pk_f16_f32 v199, v150, v151
	v_mfma_f32_16x16x32_bf16 v[144:147], v[20:23], v[68:71], v[144:147]
	v_pk_max_f16 v198, v198, 0
	v_pk_max_f16 v199, v199, 0
	v_mfma_f32_16x16x32_bf16 v[148:151], v[4:7], v[72:75], 0
	v_cvt_pk_f16_f32 v200, v152, v153
	v_cvt_pk_f16_f32 v201, v154, v155
	v_mfma_f32_16x16x32_bf16 v[148:151], v[20:23], v[76:79], v[148:151]
	v_pk_max_f16 v200, v200, 0
	v_pk_max_f16 v201, v201, 0
	v_mfma_f32_16x16x32_f16 v[128:131], v[32:35], v[196:199], 0
	v_mfma_f32_16x16x32_bf16 v[152:155], v[4:7], v[80:83], 0
	v_cvt_pk_f16_f32 v202, v156, v157
	v_cvt_pk_f16_f32 v203, v158, v159
	v_mfma_f32_16x16x32_bf16 v[152:155], v[20:23], v[84:87], v[152:155]
	v_pk_max_f16 v202, v202, 0
	v_pk_max_f16 v203, v203, 0
	v_mfma_f32_16x16x32_bf16 v[156:159], v[4:7], v[88:91], 0
	v_cvt_pk_f16_f32 v196, v144, v145
	v_cvt_pk_f16_f32 v197, v146, v147
	v_mfma_f32_16x16x32_bf16 v[156:159], v[20:23], v[92:95], v[156:159]
	v_pk_max_f16 v196, v196, 0
	v_pk_max_f16 v197, v197, 0
	v_mfma_f32_16x16x32_f16 v[128:131], v[36:39], v[200:203], v[128:131]
	v_mfma_f32_16x16x32_bf16 v[144:147], v[8:11], v[64:67], 0
	v_cvt_pk_f16_f32 v198, v148, v149
	v_cvt_pk_f16_f32 v199, v150, v151
	v_mfma_f32_16x16x32_bf16 v[144:147], v[24:27], v[68:71], v[144:147]
	v_pk_max_f16 v198, v198, 0
	v_pk_max_f16 v199, v199, 0
	v_mfma_f32_16x16x32_bf16 v[148:151], v[8:11], v[72:75], 0
	v_cvt_pk_f16_f32 v200, v152, v153
	v_cvt_pk_f16_f32 v201, v154, v155
	v_mfma_f32_16x16x32_bf16 v[148:151], v[24:27], v[76:79], v[148:151]
	v_pk_max_f16 v200, v200, 0
	v_pk_max_f16 v201, v201, 0
	v_mfma_f32_16x16x32_f16 v[132:135], v[40:43], v[196:199], 0
	v_mfma_f32_16x16x32_bf16 v[152:155], v[8:11], v[80:83], 0
	v_cvt_pk_f16_f32 v202, v156, v157
	v_cvt_pk_f16_f32 v203, v158, v159
	v_mfma_f32_16x16x32_bf16 v[152:155], v[24:27], v[84:87], v[152:155]
	v_pk_max_f16 v202, v202, 0
	v_pk_max_f16 v203, v203, 0
	v_mfma_f32_16x16x32_bf16 v[156:159], v[8:11], v[88:91], 0
	v_cvt_pk_f16_f32 v196, v144, v145
	v_cvt_pk_f16_f32 v197, v146, v147
	v_mfma_f32_16x16x32_bf16 v[156:159], v[24:27], v[92:95], v[156:159]
	v_pk_max_f16 v196, v196, 0
	v_pk_max_f16 v197, v197, 0
	v_mfma_f32_16x16x32_f16 v[132:135], v[44:47], v[200:203], v[132:135]
	v_mfma_f32_16x16x32_bf16 v[144:147], v[12:15], v[64:67], 0
	v_cvt_pk_f16_f32 v198, v148, v149
	v_cvt_pk_f16_f32 v199, v150, v151
	v_mfma_f32_16x16x32_bf16 v[144:147], v[28:31], v[68:71], v[144:147]
	v_pk_max_f16 v198, v198, 0
	v_pk_max_f16 v199, v199, 0
	v_mfma_f32_16x16x32_bf16 v[148:151], v[12:15], v[72:75], 0
	v_cvt_pk_f16_f32 v200, v152, v153
	v_cvt_pk_f16_f32 v201, v154, v155
	v_mfma_f32_16x16x32_bf16 v[148:151], v[28:31], v[76:79], v[148:151]
	v_pk_max_f16 v200, v200, 0
	v_pk_max_f16 v201, v201, 0
	v_mfma_f32_16x16x32_f16 v[136:139], v[48:51], v[196:199], 0
	v_mfma_f32_16x16x32_bf16 v[152:155], v[12:15], v[80:83], 0
	v_cvt_pk_f16_f32 v202, v156, v157
	v_cvt_pk_f16_f32 v203, v158, v159
	v_mfma_f32_16x16x32_bf16 v[152:155], v[28:31], v[84:87], v[152:155]
	v_pk_max_f16 v202, v202, 0
	v_pk_max_f16 v203, v203, 0
	v_mfma_f32_16x16x32_bf16 v[156:159], v[12:15], v[88:91], 0
	v_cvt_pk_f16_f32 v196, v144, v145
	v_cvt_pk_f16_f32 v197, v146, v147
	v_mfma_f32_16x16x32_bf16 v[156:159], v[28:31], v[92:95], v[156:159]
	v_pk_max_f16 v196, v196, 0
	v_pk_max_f16 v197, v197, 0
	v_mfma_f32_16x16x32_f16 v[136:139], v[52:55], v[200:203], v[136:139]
	v_cvt_pk_f16_f32 v198, v148, v149
	v_cvt_pk_f16_f32 v199, v150, v151
	v_pk_max_f16 v198, v198, 0
	v_pk_max_f16 v199, v199, 0
	v_cvt_pk_f16_f32 v200, v152, v153
	v_cvt_pk_f16_f32 v201, v154, v155
	v_pk_max_f16 v200, v200, 0
	v_pk_max_f16 v201, v201, 0
	v_mfma_f32_16x16x32_f16 v[140:143], v[56:59], v[196:199], 0
	v_cvt_pk_f16_f32 v202, v156, v157
	v_cvt_pk_f16_f32 v203, v158, v159
	v_pk_max_f16 v202, v202, 0
	v_pk_max_f16 v203, v203, 0
	s_nop 1
	v_mfma_f32_16x16x32_f16 v[140:143], v[60:63], v[200:203], v[140:143]
	s_nop 7
	s_cmp_lg_u32 s47, s48
	s_cbranch_scc1 .Lix_nomask0
	s_add_i32 s4, s46, 0
	v_cmp_ge_i32_e32 vcc, s4, v186
	s_nop 1
	v_cndmask_b32_e32 v128, v208, v128, vcc
	s_add_i32 s4, s46, 1
	v_cmp_ge_i32_e32 vcc, s4, v186
	s_nop 1
	v_cndmask_b32_e32 v132, v208, v132, vcc
	s_add_i32 s4, s46, 2
	v_cmp_ge_i32_e32 vcc, s4, v186
	s_nop 1
	v_cndmask_b32_e32 v136, v208, v136, vcc
	s_add_i32 s4, s46, 3
	v_cmp_ge_i32_e32 vcc, s4, v186
	s_nop 1
	v_cndmask_b32_e32 v140, v208, v140, vcc
; #define LAS __attribute__((address_space(3)))
; __device__ __forceinline__ int lane_prefix(unsigned long long mask) { return __builtin_amdgcn_mbcnt_hi((unsigned)(mask >> 32), __builtin_amdgcn_mbcnt_lo((unsigned)mask, 0)); }
; __device__ __forceinline__ void idx_append(float score, LAS float* bs, LAS unsigned* bi, int& cnt, float& tau, int kb, int t, int lane) {
;     const int kidx = kb * 64 + lane;
;     const bool valid = (kidx <= t) && (score > tau);
;     const unsigned long long vm = __ballot(valid); const int pos = cnt + lane_prefix(vm);
;     if (valid) { bs[pos] = score; bi[pos] = (unsigned)kidx; }
;     cnt += __popcll(vm);
;     __builtin_amdgcn_wave_barrier();
;     if (cnt > ICAP - 64) idx_compact(bs, bi, cnt, tau, lane);
; }
; __device__ __forceinline__ void indexer_unit(const bf16_t* IQ, const bf16_t* IK, const float* IW, unsigned short* SEL, LAS unsigned char* wlds, int t0, int lane) {
;     ...
;     for (int kb = 0; kb < nkb; kb += 2) {
;         idx_load(fb, IK, min(kb + 1, nkb - 1), n16, slab);
;         idx_wait8(fa);
;         { float sc[NQI];
; #pragma unroll
;           for (int q = 0; q < NQI; ++q) sc[q] = idx_score(fa, a0[q], a1[q], wa[q]);
; #pragma unroll
;           for (int q = 0; q < NQI; ++q) idx_append(sc[q], (LAS float*)(wlds + q * 4096), (LAS unsigned*)(wlds + q * 4096 + 2048), cnt[q], tau[q], kb, t0 + q, lane); }
;         idx_load(fa, IK, min(kb + 2, nkb - 1), n16, slab);
;         idx_wait8(fb);
.Lix_nomask0:
	v_cmp_lt_f32_e64 s[0:1], s58, v128
	s_cmp_eq_u64 s[0:1], 0
	s_cbranch_scc1 .Lix_skip0
	s_mov_b64 s[4:5], exec
	s_mov_b64 exec, s[0:1]
	v_mbcnt_lo_u32_b32 v190, s0, 0
	v_mbcnt_hi_u32_b32 v190, s1, v190
	v_add_u32_e32 v190, s52, v190
	v_lshl_add_u32 v190, v190, 2, s82
	ds_write2st64_b32 v190, v128, v186 offset0:0 offset1:8
	s_mov_b64 exec, s[4:5]
	s_bcnt1_i32_b64 s0, s[0:1]
	s_add_i32 s52, s52, s0
.Lix_skip0:
	v_cmp_lt_f32_e64 s[0:1], s59, v132
	s_cmp_eq_u64 s[0:1], 0
	s_cbranch_scc1 .Lix_skip1
	s_mov_b64 s[4:5], exec
	s_mov_b64 exec, s[0:1]
	v_mbcnt_lo_u32_b32 v190, s0, 0
	v_mbcnt_hi_u32_b32 v190, s1, v190
	v_add_u32_e32 v190, s53, v190
	v_lshl_add_u32 v190, v190, 2, s82
	ds_write2st64_b32 v190, v132, v186 offset0:16 offset1:24
	s_mov_b64 exec, s[4:5]
	s_bcnt1_i32_b64 s0, s[0:1]
	s_add_i32 s53, s53, s0
.Lix_skip1:
	v_cmp_lt_f32_e64 s[0:1], s60, v136
	s_cmp_eq_u64 s[0:1], 0
	s_cbranch_scc1 .Lix_skip2
	s_mov_b64 s[4:5], exec
	s_mov_b64 exec, s[0:1]
	v_mbcnt_lo_u32_b32 v190, s0, 0
	v_mbcnt_hi_u32_b32 v190, s1, v190
	v_add_u32_e32 v190, s54, v190
	v_lshl_add_u32 v190, v190, 2, s82
	ds_write2st64_b32 v190, v136, v186 offset0:32 offset1:40
	s_mov_b64 exec, s[4:5]
	s_bcnt1_i32_b64 s0, s[0:1]
	s_add_i32 s54, s54, s0
.Lix_skip2:
	v_cmp_lt_f32_e64 s[0:1], s61, v140
	s_cmp_eq_u64 s[0:1], 0
	s_cbranch_scc1 .Lix_skip3
	s_mov_b64 s[4:5], exec
	s_mov_b64 exec, s[0:1]
	v_mbcnt_lo_u32_b32 v190, s0, 0
	v_mbcnt_hi_u32_b32 v190, s1, v190
	v_add_u32_e32 v190, s55, v190
	v_lshl_add_u32 v190, v190, 2, s82
	ds_write2st64_b32 v190, v140, v186 offset0:48 offset1:56
	s_mov_b64 exec, s[4:5]
	s_bcnt1_i32_b64 s0, s[0:1]
	s_add_i32 s55, s55, s0
.Lix_skip3:
	v_add_u32_e32 v186, 64, v186
	s_mov_b32 s0, 0
	s_cmpk_gt_i32 s52, 0x1c0
	s_cselect_b32 s1, 1, 0
	s_or_b32 s0, s0, s1
	s_cmpk_gt_i32 s53, 0x1c0
	s_cselect_b32 s1, 2, 0
	s_or_b32 s0, s0, s1
	s_cmpk_gt_i32 s54, 0x1c0
	s_cselect_b32 s1, 4, 0
	s_or_b32 s0, s0, s1
	s_cmpk_gt_i32 s55, 0x1c0
	s_cselect_b32 s1, 8, 0
	s_or_b32 s0, s0, s1
	s_cmp_eq_u32 s0, 0
	s_cbranch_scc1 .Lix_noreq0
	v_mov_b32_e32 v190, s101
	v_mov_b32_e32 v191, s0
	s_mov_b64 s[4:5], exec
	s_mov_b64 exec, 1
	ds_or_b32 v190, v191
	s_mov_b64 exec, s[4:5]
	s_waitcnt lgkmcnt(0)
.Lix_noreq0:
	s_mov_b32 s0, s13
	s_mov_b32 s13, s101
	s_mov_b32 s101, s50
	s_mov_b32 s50, s0
	s_add_i32 s47, s47, 1
	s_cmp_gt_i32 s47, s48
	s_cbranch_scc1 .Lix_done
	s_waitcnt vmcnt(0)
	s_barrier
	v_mov_b32_e32 v190, s13
	ds_read_b32 v191, v190
	ds_read_b128 v[64:67], v98 offset:0
	ds_read_b128 v[68:71], v99 offset:0
	ds_read_b128 v[72:75], v98 offset:2048
	ds_read_b128 v[76:79], v99 offset:2048
	ds_read_b128 v[80:83], v98 offset:4096
	ds_read_b128 v[84:87], v99 offset:4096
	ds_read_b128 v[88:91], v98 offset:6144
	ds_read_b128 v[92:95], v99 offset:6144
	s_cmp_ge_u32 s47, s48
	s_cbranch_scc1 .Lix_nodma1
	s_add_u32 s76, s76, 0x2000
	s_addc_u32 s77, s77, 0
	s_lshr_b32 s0, s82, 4
	s_add_i32 m0, s0, 147456
	s_nop 0
	global_load_lds_dwordx4 v185, s[76:77]

; #define LAS __attribute__((address_space(3)))
; __device__ __forceinline__ int lane_prefix(unsigned long long mask) { return __builtin_amdgcn_mbcnt_hi((unsigned)(mask >> 32), __builtin_amdgcn_mbcnt_lo((unsigned)mask, 0)); }
; __device__ __forceinline__ void idx_append(float score, LAS float* bs, LAS unsigned* bi, int& cnt, float& tau, int kb, int t, int lane) {
;     const int kidx = kb * 64 + lane;
;     const bool valid = (kidx <= t) && (score > tau);
;     const unsigned long long vm = __ballot(valid); const int pos = cnt + lane_prefix(vm);
;     if (valid) { bs[pos] = score; bi[pos] = (unsigned)kidx; }
;     cnt += __popcll(vm);
;     __builtin_amdgcn_wave_barrier();
;     if (cnt > ICAP - 64) idx_compact(bs, bi, cnt, tau, lane);
; }
.Lix_noclr1:
	s_waitcnt lgkmcnt(0)
	v_readfirstlane_b32 s49, v191
	s_nop 3
	s_cmp_eq_u32 s49, 0
	s_cbranch_scc1 .Lix_nocomp1
	s_bitcmp1_b32 s49, 0
	s_cbranch_scc0 .Lix_ncq1_0
	s_cmpk_lt_i32 s52, 0x141
	s_cbranch_scc1 .Lix_ncq1_0
	s_add_i32 s79, s82, 0
	s_mov_b32 s80, s52
	s_mov_b32 s56, s28
	s_movk_i32 s19, 288
	s_mov_b32 s78, 4
	s_branch .Lix_compact

; #define LAS __attribute__((address_space(3)))
; __device__ __forceinline__ int lane_prefix(unsigned long long mask) { return __builtin_amdgcn_mbcnt_hi((unsigned)(mask >> 32), __builtin_amdgcn_mbcnt_lo((unsigned)mask, 0)); }
; __device__ __forceinline__ void idx_append(float score, LAS float* bs, LAS unsigned* bi, int& cnt, float& tau, int kb, int t, int lane) {
;     const int kidx = kb * 64 + lane;
;     const bool valid = (kidx <= t) && (score > tau);
;     const unsigned long long vm = __ballot(valid); const int pos = cnt + lane_prefix(vm);
;     if (valid) { bs[pos] = score; bi[pos] = (unsigned)kidx; }
;     cnt += __popcll(vm);
;     __builtin_amdgcn_wave_barrier();
;     if (cnt > ICAP - 64) idx_compact(bs, bi, cnt, tau, lane);
; }
.Lix_ncq1_0:
	s_bitcmp1_b32 s49, 1
	s_cbranch_scc0 .Lix_ncq1_1
	s_cmpk_lt_i32 s53, 0x141
	s_cbranch_scc1 .Lix_ncq1_1
	s_add_i32 s79, s82, 4096
	s_mov_b32 s80, s53
	s_mov_b32 s56, s29
	s_movk_i32 s19, 288
	s_mov_b32 s78, 5
	s_branch .Lix_compact

; #define LAS __attribute__((address_space(3)))
; __device__ __forceinline__ int lane_prefix(unsigned long long mask) { return __builtin_amdgcn_mbcnt_hi((unsigned)(mask >> 32), __builtin_amdgcn_mbcnt_lo((unsigned)mask, 0)); }
; __device__ __forceinline__ void idx_append(float score, LAS float* bs, LAS unsigned* bi, int& cnt, float& tau, int kb, int t, int lane) {
;     const int kidx = kb * 64 + lane;
;     const bool valid = (kidx <= t) && (score > tau);
;     const unsigned long long vm = __ballot(valid); const int pos = cnt + lane_prefix(vm);
;     if (valid) { bs[pos] = score; bi[pos] = (unsigned)kidx; }
;     cnt += __popcll(vm);
;     __builtin_amdgcn_wave_barrier();
;     if (cnt > ICAP - 64) idx_compact(bs, bi, cnt, tau, lane);
; }
.Lix_ncq1_1:
	s_bitcmp1_b32 s49, 2
	s_cbranch_scc0 .Lix_ncq1_2
	s_cmpk_lt_i32 s54, 0x141
	s_cbranch_scc1 .Lix_ncq1_2
	s_add_i32 s79, s82, 8192
	s_mov_b32 s80, s54
	s_mov_b32 s56, s34
	s_movk_i32 s19, 288
	s_mov_b32 s78, 6
	s_branch .Lix_compact

; #define LAS __attribute__((address_space(3)))
; __device__ __forceinline__ int lane_prefix(unsigned long long mask) { return __builtin_amdgcn_mbcnt_hi((unsigned)(mask >> 32), __builtin_amdgcn_mbcnt_lo((unsigned)mask, 0)); }
; __device__ __forceinline__ void idx_append(float score, LAS float* bs, LAS unsigned* bi, int& cnt, float& tau, int kb, int t, int lane) {
;     const int kidx = kb * 64 + lane;
;     const bool valid = (kidx <= t) && (score > tau);
;     const unsigned long long vm = __ballot(valid); const int pos = cnt + lane_prefix(vm);
;     if (valid) { bs[pos] = score; bi[pos] = (unsigned)kidx; }
;     cnt += __popcll(vm);
;     __builtin_amdgcn_wave_barrier();
;     if (cnt > ICAP - 64) idx_compact(bs, bi, cnt, tau, lane);
; }
.Lix_ncq1_2:
	s_bitcmp1_b32 s49, 3
	s_cbranch_scc0 .Lix_ncq1_3
	s_cmpk_lt_i32 s55, 0x141
	s_cbranch_scc1 .Lix_ncq1_3
	s_add_i32 s79, s82, 12288
	s_mov_b32 s80, s55
	s_mov_b32 s56, s35
	s_movk_i32 s19, 288
	s_mov_b32 s78, 7
	s_branch .Lix_compact

; #define LAS __attribute__((address_space(3)))
; __device__ __forceinline__ void indexer_unit(const bf16_t* IQ, const bf16_t* IK, const float* IW, unsigned short* SEL, LAS unsigned char* wlds, int t0, int lane) {
;     ...
;         if (kb + 1 < nkb) {
;             float sc[NQI];
; #pragma unroll
;             for (int q = 0; q < NQI; ++q) sc[q] = idx_score(fb, a0[q], a1[q], wa[q]);
; #pragma unroll
;             for (int q = 0; q < NQI; ++q) idx_append(sc[q], (LAS float*)(wlds + q * 4096), (LAS unsigned*)(wlds + q * 4096 + 2048), cnt[q], tau[q], kb + 1, t0 + q, lane);
;         }
;     }
;     idx_wait0(fa, fb);
; #pragma unroll
;     for (int q = 0; q < NQI; ++q) {
;         LAS float* bs = (LAS float*)(wlds + q * 4096); LAS unsigned* bi = (LAS unsigned*)(wlds + q * 4096 + 2048);
;         if (cnt[q] > 256) idx_compact(bs, bi, cnt[q], tau[q], lane);
.Lix_noreq1:
	s_mov_b32 s0, s13
	s_mov_b32 s13, s101
	s_mov_b32 s101, s50
	s_mov_b32 s50, s0
	s_add_i32 s47, s47, 1
	s_cmp_le_i32 s47, s48
	s_cbranch_scc1 .Lix_loop
.Lix_done:
	s_cmpk_lt_i32 s52, 0x101
	s_cbranch_scc1 .Lix_fin0
	s_add_i32 s79, s82, 0
	s_mov_b32 s80, s52
	s_mov_b32 s56, s28
	s_movk_i32 s19, 256
	s_mov_b32 s78, 8
	s_branch .Lix_compact

; #define LAS __attribute__((address_space(3)))
; __device__ __forceinline__ void indexer_unit(const bf16_t* IQ, const bf16_t* IK, const float* IW, unsigned short* SEL, LAS unsigned char* wlds, int t0, int lane) {
;     ...
; #pragma unroll
;     for (int q = 0; q < NQI; ++q) {
;         LAS float* bs = (LAS float*)(wlds + q * 4096); LAS unsigned* bi = (LAS unsigned*)(wlds + q * 4096 + 2048);
;         if (cnt[q] > 256) idx_compact(bs, bi, cnt[q], tau[q], lane);
;         __builtin_amdgcn_wave_barrier();
;         unsigned short* sel = SEL + (size_t)(t0 + q) * 256;
; #pragma unroll
;         for (int j = 0; j < 4; ++j) { const int e = j * 64 + lane; if (e < cnt[q]) sel[e] = (unsigned short)bi[e]; }
;     }
.Lix_fin0:
	s_add_i32 s0, s46, 0
	s_lshl_b32 s0, s0, 9
	s_add_u32 s0, s44, s0
	s_addc_u32 s1, s45, 0
	ds_read2st64_b32 v[190:191], v187 offset0:8 offset1:9
	ds_read2st64_b32 v[192:193], v187 offset0:10 offset1:11
	s_mov_b64 s[4:5], exec
	s_waitcnt lgkmcnt(0)
	s_sub_i32 s19, s52, 0
	v_cmp_gt_i32_e32 vcc, s19, v182
	s_nop 1
	s_and_b64 exec, s[4:5], vcc
	global_store_short v189, v190, s[0:1]
	s_sub_i32 s19, s52, 64
	v_cmp_gt_i32_e32 vcc, s19, v182
	s_nop 1
	s_and_b64 exec, s[4:5], vcc
	global_store_short v189, v191, s[0:1] offset:128
	s_sub_i32 s19, s52, 128
	v_cmp_gt_i32_e32 vcc, s19, v182
	s_nop 1
	s_and_b64 exec, s[4:5], vcc
	global_store_short v189, v192, s[0:1] offset:256
	s_sub_i32 s19, s52, 192
	v_cmp_gt_i32_e32 vcc, s19, v182
	s_nop 1
	s_and_b64 exec, s[4:5], vcc
	global_store_short v189, v193, s[0:1] offset:384
	s_mov_b64 exec, s[4:5]
	s_cmpk_lt_i32 s53, 0x101
	s_cbranch_scc1 .Lix_fin1
	s_add_i32 s79, s82, 4096
	s_mov_b32 s80, s53
	s_mov_b32 s56, s29
	s_movk_i32 s19, 256
	s_mov_b32 s78, 9
	s_branch .Lix_compact

; #define LAS __attribute__((address_space(3)))
; __device__ __forceinline__ void indexer_unit(const bf16_t* IQ, const bf16_t* IK, const float* IW, unsigned short* SEL, LAS unsigned char* wlds, int t0, int lane) {
;     ...
; #pragma unroll
;     for (int q = 0; q < NQI; ++q) {
;         LAS float* bs = (LAS float*)(wlds + q * 4096); LAS unsigned* bi = (LAS unsigned*)(wlds + q * 4096 + 2048);
;         if (cnt[q] > 256) idx_compact(bs, bi, cnt[q], tau[q], lane);
;         __builtin_amdgcn_wave_barrier();
;         unsigned short* sel = SEL + (size_t)(t0 + q) * 256;
; #pragma unroll
;         for (int j = 0; j < 4; ++j) { const int e = j * 64 + lane; if (e < cnt[q]) sel[e] = (unsigned short)bi[e]; }
;     }
.Lix_fin1:
	s_add_i32 s0, s46, 1
	s_lshl_b32 s0, s0, 9
	s_add_u32 s0, s44, s0
	s_addc_u32 s1, s45, 0
	ds_read2st64_b32 v[190:191], v187 offset0:24 offset1:25
	ds_read2st64_b32 v[192:193], v187 offset0:26 offset1:27
	s_mov_b64 s[4:5], exec
	s_waitcnt lgkmcnt(0)
	s_sub_i32 s19, s53, 0
	v_cmp_gt_i32_e32 vcc, s19, v182
	s_nop 1
	s_and_b64 exec, s[4:5], vcc
	global_store_short v189, v190, s[0:1]
	s_sub_i32 s19, s53, 64
	v_cmp_gt_i32_e32 vcc, s19, v182
	s_nop 1
	s_and_b64 exec, s[4:5], vcc
	global_store_short v189, v191, s[0:1] offset:128
	s_sub_i32 s19, s53, 128
	v_cmp_gt_i32_e32 vcc, s19, v182
	s_nop 1
	s_and_b64 exec, s[4:5], vcc
	global_store_short v189, v192, s[0:1] offset:256
	s_sub_i32 s19, s53, 192
	v_cmp_gt_i32_e32 vcc, s19, v182
	s_nop 1
	s_and_b64 exec, s[4:5], vcc
	global_store_short v189, v193, s[0:1] offset:384
	s_mov_b64 exec, s[4:5]
	s_cmpk_lt_i32 s54, 0x101
	s_cbranch_scc1 .Lix_fin2
	s_add_i32 s79, s82, 8192
	s_mov_b32 s80, s54
	s_mov_b32 s56, s34
	s_movk_i32 s19, 256
	s_mov_b32 s78, 10
	s_branch .Lix_compact

; #define LAS __attribute__((address_space(3)))
; __device__ __forceinline__ void indexer_unit(const bf16_t* IQ, const bf16_t* IK, const float* IW, unsigned short* SEL, LAS unsigned char* wlds, int t0, int lane) {
;     ...
; #pragma unroll
;     for (int q = 0; q < NQI; ++q) {
;         LAS float* bs = (LAS float*)(wlds + q * 4096); LAS unsigned* bi = (LAS unsigned*)(wlds + q * 4096 + 2048);
;         if (cnt[q] > 256) idx_compact(bs, bi, cnt[q], tau[q], lane);
;         __builtin_amdgcn_wave_barrier();
;         unsigned short* sel = SEL + (size_t)(t0 + q) * 256;
; #pragma unroll
;         for (int j = 0; j < 4; ++j) { const int e = j * 64 + lane; if (e < cnt[q]) sel[e] = (unsigned short)bi[e]; }
;     }
.Lix_fin2:
	s_add_i32 s0, s46, 2
	s_lshl_b32 s0, s0, 9
	s_add_u32 s0, s44, s0
	s_addc_u32 s1, s45, 0
	ds_read2st64_b32 v[190:191], v187 offset0:40 offset1:41
	ds_read2st64_b32 v[192:193], v187 offset0:42 offset1:43
	s_mov_b64 s[4:5], exec
	s_waitcnt lgkmcnt(0)
	s_sub_i32 s19, s54, 0
	v_cmp_gt_i32_e32 vcc, s19, v182
	s_nop 1
	s_and_b64 exec, s[4:5], vcc
	global_store_short v189, v190, s[0:1]
	s_sub_i32 s19, s54, 64
	v_cmp_gt_i32_e32 vcc, s19, v182
	s_nop 1
	s_and_b64 exec, s[4:5], vcc
	global_store_short v189, v191, s[0:1] offset:128
	s_sub_i32 s19, s54, 128
	v_cmp_gt_i32_e32 vcc, s19, v182
	s_nop 1
	s_and_b64 exec, s[4:5], vcc
	global_store_short v189, v192, s[0:1] offset:256
	s_sub_i32 s19, s54, 192
	v_cmp_gt_i32_e32 vcc, s19, v182
	s_nop 1
	s_and_b64 exec, s[4:5], vcc
	global_store_short v189, v193, s[0:1] offset:384
	s_mov_b64 exec, s[4:5]
	s_cmpk_lt_i32 s55, 0x101
	s_cbranch_scc1 .Lix_fin3
	s_add_i32 s79, s82, 12288
	s_mov_b32 s80, s55
	s_mov_b32 s56, s35
	s_movk_i32 s19, 256
	s_mov_b32 s78, 11
	s_branch .Lix_compact

; #define LAS __attribute__((address_space(3)))
; __device__ __forceinline__ void idx_compact(LAS float* bs, LAS unsigned* bi, int& cnt, float& tau, int lane) {
;     unsigned u[ICAP / 64], id[ICAP / 64];
; #pragma unroll
;     for (int i = 0; i < ICAP / 64; ++i) { const int e = i * 64 + lane; const bool in = e < cnt; u[i] = in ? f2sort(bs[e]) : 0u; id[i] = in ? bi[e] : 0u; }
;     unsigned T = 0u;
; #pragma unroll 1
;     ...
; #pragma unroll
;         for (int i = 0; i < ICAP / 64; ++i) c += __popcll(__ballot(u[i] >= cand));
;         if (c >= 256) T = cand; if (c == 256) break; }
; __device__ __forceinline__ void indexer_unit(const bf16_t* IQ, const bf16_t* IK, const float* IW, unsigned short* SEL, LAS unsigned char* wlds, int t0, int lane) {
;     ...
; #pragma unroll
;     for (int q = 0; q < NQI; ++q) {
;         LAS float* bs = (LAS float*)(wlds + q * 4096); LAS unsigned* bi = (LAS unsigned*)(wlds + q * 4096 + 2048);
;         if (cnt[q] > 256) idx_compact(bs, bi, cnt[q], tau[q], lane);
;         __builtin_amdgcn_wave_barrier();
;         unsigned short* sel = SEL + (size_t)(t0 + q) * 256;
; #pragma unroll
;         for (int j = 0; j < 4; ++j) { const int e = j * 64 + lane; if (e < cnt[q]) sel[e] = (unsigned short)bi[e]; }
;     }
; __global__ void __launch_bounds__(NTHREADS, 2) mega(Args a) {
;     ...
;                 for (int rep = 0; rep < REP_IDX; ++rep) for (int pr = gw; pr < SEQ / NQI / 2; pr += NGW) {
;                     indexer_unit(IQ, IK, IW, SEL, lds + wave * 16384, (SEQ / NQI - 1 - pr) * NQI, lane); indexer_unit(IQ, IK, IW, SEL, lds + wave * 16384, pr * NQI, lane); }
.Lix_fin3:
	s_add_i32 s0, s46, 3
	s_lshl_b32 s0, s0, 9
	s_add_u32 s0, s44, s0
	s_addc_u32 s1, s45, 0
	ds_read2st64_b32 v[190:191], v187 offset0:56 offset1:57
	ds_read2st64_b32 v[192:193], v187 offset0:58 offset1:59
	s_mov_b64 s[4:5], exec
	s_waitcnt lgkmcnt(0)
	s_sub_i32 s19, s55, 0
	v_cmp_gt_i32_e32 vcc, s19, v182
	s_nop 1
	s_and_b64 exec, s[4:5], vcc
	global_store_short v189, v190, s[0:1]
	s_sub_i32 s19, s55, 64
	v_cmp_gt_i32_e32 vcc, s19, v182
	s_nop 1
	s_and_b64 exec, s[4:5], vcc
	global_store_short v189, v191, s[0:1] offset:128
	s_sub_i32 s19, s55, 128
	v_cmp_gt_i32_e32 vcc, s19, v182
	s_nop 1
	s_and_b64 exec, s[4:5], vcc
	global_store_short v189, v192, s[0:1] offset:256
	s_sub_i32 s19, s55, 192
	v_cmp_gt_i32_e32 vcc, s19, v182
	s_nop 1
	s_and_b64 exec, s[4:5], vcc
	global_store_short v189, v193, s[0:1] offset:384
	s_mov_b64 exec, s[4:5]
	v_readlane_b32 s0, v249, 1
	v_readlane_b32 s1, v249, 0
	s_nop 3
	s_cmp_eq_u32 s0, 1
	s_cbranch_scc1 .Lix_pair_next
	s_mov_b32 s0, 1
	v_writelane_b32 v249, s0, 1
	s_lshr_b32 s0, s82, 14
	s_add_i32 s1, s1, s0
	s_lshl_b32 s46, s1, 2
	s_branch .Lix_unit
.Lix_pair_next:
	s_add_i32 s1, s1, s66
	v_writelane_b32 v249, s1, 0
	s_cmpk_lt_i32 s1, 0x800
	s_cbranch_scc1 .Lix_pair
	s_branch .Lix_exit
.Lix_compact:
	v_add_u32_e32 v193, s79, v187
	v_subrev_u32_e32 v193, s82, v193
	ds_read2st64_b32 v[240:241], v193 offset0:0 offset1:1
	ds_read2st64_b32 v[242:243], v193 offset0:2 offset1:3
	ds_read2st64_b32 v[244:245], v193 offset0:4 offset1:5
	ds_read2st64_b32 v[246:247], v193 offset0:6 offset1:7
	ds_read2st64_b32 v[214:215], v193 offset0:8 offset1:9
	ds_read2st64_b32 v[216:217], v193 offset0:10 offset1:11
	ds_read2st64_b32 v[218:219], v193 offset0:12 offset1:13
	ds_read2st64_b32 v[220:221], v193 offset0:14 offset1:15
	s_waitcnt lgkmcnt(0)
	v_ashrrev_i32_e32 v190, 31, v240
	s_sub_i32 s0, s80, 0
	v_or_b32_e32 v190, 0x80000000, v190
	v_cmp_gt_i32_e32 vcc, s0, v182
	v_xor_b32_e32 v194, v240, v190
	s_nop 0
	v_cndmask_b32_e32 v194, 0, v194, vcc
	v_ashrrev_i32_e32 v190, 31, v241
	s_sub_i32 s0, s80, 64
	v_or_b32_e32 v190, 0x80000000, v190
	v_cmp_gt_i32_e32 vcc, s0, v182
	v_xor_b32_e32 v195, v241, v190
	s_nop 0
	v_cndmask_b32_e32 v195, 0, v195, vcc
	v_ashrrev_i32_e32 v190, 31, v242
	s_sub_i32 s0, s80, 128
	v_or_b32_e32 v190, 0x80000000, v190
	v_cmp_gt_i32_e32 vcc, s0, v182
	v_xor_b32_e32 v196, v242, v190
	s_nop 0
	v_cndmask_b32_e32 v196, 0, v196, vcc
	v_ashrrev_i32_e32 v190, 31, v243
	s_sub_i32 s0, s80, 192
	v_or_b32_e32 v190, 0x80000000, v190
	v_cmp_gt_i32_e32 vcc, s0, v182
	v_xor_b32_e32 v197, v243, v190
	s_nop 0
	v_cndmask_b32_e32 v197, 0, v197, vcc
	v_ashrrev_i32_e32 v190, 31, v244
	s_sub_i32 s0, s80, 256
	v_or_b32_e32 v190, 0x80000000, v190
	v_cmp_gt_i32_e32 vcc, s0, v182
	v_xor_b32_e32 v198, v244, v190
	s_nop 0
	v_cndmask_b32_e32 v198, 0, v198, vcc
	v_ashrrev_i32_e32 v190, 31, v245
	s_sub_i32 s0, s80, 320
	v_or_b32_e32 v190, 0x80000000, v190
	v_cmp_gt_i32_e32 vcc, s0, v182
	v_xor_b32_e32 v199, v245, v190
	s_nop 0
	v_cndmask_b32_e32 v199, 0, v199, vcc
	v_ashrrev_i32_e32 v190, 31, v246
	s_sub_i32 s0, s80, 384
	v_or_b32_e32 v190, 0x80000000, v190
	v_cmp_gt_i32_e32 vcc, s0, v182
	v_xor_b32_e32 v200, v246, v190
	s_nop 0
	v_cndmask_b32_e32 v200, 0, v200, vcc
	v_ashrrev_i32_e32 v190, 31, v247
	s_sub_i32 s0, s80, 448
	v_or_b32_e32 v190, 0x80000000, v190
	v_cmp_gt_i32_e32 vcc, s0, v182
	v_xor_b32_e32 v201, v247, v190
	s_nop 0
	v_cndmask_b32_e32 v201, 0, v201, vcc
	v_max_u32_e32 v190, v194, v195
	v_max3_u32 v190, v190, v196, v197
	v_max3_u32 v190, v190, v198, v199
	v_max3_u32 v190, v190, v200, v201
	s_nop 1
	v_max_u32_dpp v190, v190, v190 row_ror:8 row_mask:0xf bank_mask:0xf bound_ctrl:1
	s_nop 1
	v_max_u32_dpp v190, v190, v190 row_ror:4 row_mask:0xf bank_mask:0xf bound_ctrl:1
	s_nop 1
	v_max_u32_dpp v190, v190, v190 quad_perm:[2,3,0,1] row_mask:0xf bank_mask:0xf bound_ctrl:1
	s_nop 1
	v_max_u32_dpp v190, v190, v190 quad_perm:[1,0,3,2] row_mask:0xf bank_mask:0xf bound_ctrl:1
	v_mov_b32_e32 v191, v190
	s_nop 1
	v_permlane16_swap_b32_e32 v190, v191
	s_nop 1
	v_max_u32_e32 v190, v190, v191
	v_mov_b32_e32 v191, v190
	s_nop 1
	v_permlane32_swap_b32_e32 v190, v191
	s_nop 1
	v_max_u32_e32 v190, v190, v191
	s_nop 1
	v_readfirstlane_b32 s0, v190
	s_mov_b32 s100, s80
	s_nop 2
	s_xor_b32 s1, s0, s56
	s_cmp_eq_u32 s1, 0
	s_cbranch_scc1 .Lix_cs_done
	s_flbit_i32_b32 s1, s1
	s_lshr_b32 s0, -1, s1
	s_andn2_b32 s56, s56, s0
	s_sub_i32 s83, 31, s1
.Lix_cs_loop:
	s_lshl_b32 s51, 1, s83
	s_or_b32 s51, s51, s56
	v_cmp_le_u32_e64 s[64:65], s51, v194
	v_cmp_le_u32_e64 s[30:31], s51, v195
	v_cmp_le_u32_e64 s[36:37], s51, v196
	v_cmp_le_u32_e64 s[62:63], s51, v197
	v_cmp_le_u32_e64 s[68:69], s51, v198
	v_cmp_le_u32_e64 s[70:71], s51, v199
	v_cmp_le_u32_e64 s[72:73], s51, v200
	v_cmp_le_u32_e64 s[74:75], s51, v201
	s_bcnt1_i32_b64 s0, s[64:65]
	s_bcnt1_i32_b64 s1, s[30:31]
	s_add_i32 s0, s0, s1
	s_bcnt1_i32_b64 s1, s[36:37]
	s_add_i32 s0, s0, s1
	s_bcnt1_i32_b64 s1, s[62:63]
	s_add_i32 s0, s0, s1
	s_bcnt1_i32_b64 s1, s[68:69]
	s_add_i32 s0, s0, s1
	s_bcnt1_i32_b64 s1, s[70:71]
	s_add_i32 s0, s0, s1
	s_bcnt1_i32_b64 s1, s[72:73]
	s_add_i32 s0, s0, s1
	s_bcnt1_i32_b64 s1, s[74:75]
	s_add_i32 s0, s0, s1
	s_cmpk_gt_u32 s0, 0xff
	s_cselect_b32 s56, s51, s56
	s_cselect_b32 s100, s0, s100
	s_cbranch_scc0 .Lix_cs_next
	s_cmp_le_u32 s0, s19
	s_cbranch_scc1 .Lix_cs_done
.Lix_cs_next:
	s_sub_i32 s83, s83, 1
	s_cmp_ge_i32 s83, 0
	s_cbranch_scc1 .Lix_cs_loop
; __device__ __forceinline__ int lane_prefix(unsigned long long mask) { return __builtin_amdgcn_mbcnt_hi((unsigned)(mask >> 32), __builtin_amdgcn_mbcnt_lo((unsigned)mask, 0)); }
; __device__ __forceinline__ void idx_compact(LAS float* bs, LAS unsigned* bi, int& cnt, float& tau, int lane) {
;     ...
;     int ngt = 0;
; #pragma unroll
;     for (int i = 0; i < ICAP / 64; ++i) ngt += __popcll(__ballot(u[i] > T));
;     const int need_eq = 256 - ngt;
;     int base = 0, eqbase = 0;
;     __builtin_amdgcn_wave_barrier();
; #pragma unroll
;     for (int i = 0; i < ICAP / 64; ++i) {
;         const bool gt = u[i] > T, eq = u[i] == T;
;         const unsigned long long em = __ballot(eq); const int eqpos = eqbase + lane_prefix(em); eqbase += __popcll(em);
;         const bool keep = gt || (eq && eqpos < need_eq);
;         const unsigned long long km = __ballot(keep); const int pos = base + lane_prefix(km); base += __popcll(km);
;         if (keep) { bs[pos] = sort2f(u[i]); bi[pos] = id[i]; }
;     }
;     __builtin_amdgcn_wave_barrier();
;     cnt = 256; tau = sort2f(T);
; }
.Lix_cs_done:
	v_cmp_lt_u32_e64 s[64:65], s56, v194
	v_cmp_lt_u32_e64 s[30:31], s56, v195
	v_cmp_lt_u32_e64 s[36:37], s56, v196
	v_cmp_lt_u32_e64 s[62:63], s56, v197
	v_cmp_lt_u32_e64 s[68:69], s56, v198
	v_cmp_lt_u32_e64 s[70:71], s56, v199
	v_cmp_lt_u32_e64 s[72:73], s56, v200
	v_cmp_lt_u32_e64 s[74:75], s56, v201
	s_bcnt1_i32_b64 s0, s[64:65]
	s_bcnt1_i32_b64 s1, s[30:31]
	s_add_i32 s0, s0, s1
	s_bcnt1_i32_b64 s1, s[36:37]
	s_add_i32 s0, s0, s1
	s_bcnt1_i32_b64 s1, s[62:63]
	s_add_i32 s0, s0, s1
	s_bcnt1_i32_b64 s1, s[68:69]
	s_add_i32 s0, s0, s1
	s_bcnt1_i32_b64 s1, s[70:71]
	s_add_i32 s0, s0, s1
	s_bcnt1_i32_b64 s1, s[72:73]
	s_add_i32 s0, s0, s1
	s_bcnt1_i32_b64 s1, s[74:75]
	s_add_i32 s0, s0, s1
	s_cmp_le_u32 s100, s19
	s_cselect_b32 s80, s100, 0x100
	s_sub_i32 s19, s80, s0
	s_mov_b32 s98, 0
	s_mov_b32 s99, 0
	s_mov_b64 s[4:5], exec
	v_cmp_eq_u32_e64 s[0:1], s56, v194
	s_nop 1
	v_mbcnt_lo_u32_b32 v190, s0, 0
	v_mbcnt_hi_u32_b32 v190, s1, v190
	v_add_u32_e32 v190, s98, v190
	v_cmp_gt_i32_e32 vcc, s19, v190
	s_bcnt1_i32_b64 s83, s[0:1]
	s_add_i32 s98, s98, s83
	s_and_b64 s[0:1], s[0:1], vcc
	s_or_b64 s[0:1], s[0:1], s[64:65]
	v_mbcnt_lo_u32_b32 v191, s0, 0
	v_mbcnt_hi_u32_b32 v191, s1, v191
	v_add_u32_e32 v191, s99, v191
	v_lshl_add_u32 v191, v191, 2, s79
	s_mov_b64 exec, s[0:1]
	ds_write2st64_b32 v191, v240, v214 offset1:8
	s_mov_b64 exec, s[4:5]
	s_bcnt1_i32_b64 s83, s[0:1]
	s_add_i32 s99, s99, s83
	v_cmp_eq_u32_e64 s[0:1], s56, v195
	s_nop 1
	v_mbcnt_lo_u32_b32 v190, s0, 0
	v_mbcnt_hi_u32_b32 v190, s1, v190
	v_add_u32_e32 v190, s98, v190
	v_cmp_gt_i32_e32 vcc, s19, v190
	s_bcnt1_i32_b64 s83, s[0:1]
	s_add_i32 s98, s98, s83
	s_and_b64 s[0:1], s[0:1], vcc
	s_or_b64 s[0:1], s[0:1], s[30:31]
	v_mbcnt_lo_u32_b32 v191, s0, 0
	v_mbcnt_hi_u32_b32 v191, s1, v191
	v_add_u32_e32 v191, s99, v191
	v_lshl_add_u32 v191, v191, 2, s79
	s_mov_b64 exec, s[0:1]
	ds_write2st64_b32 v191, v241, v215 offset1:8
	s_mov_b64 exec, s[4:5]
	s_bcnt1_i32_b64 s83, s[0:1]
	s_add_i32 s99, s99, s83
	v_cmp_eq_u32_e64 s[0:1], s56, v196
	s_nop 1
	v_mbcnt_lo_u32_b32 v190, s0, 0
	v_mbcnt_hi_u32_b32 v190, s1, v190
	v_add_u32_e32 v190, s98, v190
	v_cmp_gt_i32_e32 vcc, s19, v190
	s_bcnt1_i32_b64 s83, s[0:1]
	s_add_i32 s98, s98, s83
	s_and_b64 s[0:1], s[0:1], vcc
	s_or_b64 s[0:1], s[0:1], s[36:37]
	v_mbcnt_lo_u32_b32 v191, s0, 0
	v_mbcnt_hi_u32_b32 v191, s1, v191
	v_add_u32_e32 v191, s99, v191
	v_lshl_add_u32 v191, v191, 2, s79
	s_mov_b64 exec, s[0:1]
	ds_write2st64_b32 v191, v242, v216 offset1:8
	s_mov_b64 exec, s[4:5]
	s_bcnt1_i32_b64 s83, s[0:1]
	s_add_i32 s99, s99, s83
	v_cmp_eq_u32_e64 s[0:1], s56, v197
	s_nop 1
	v_mbcnt_lo_u32_b32 v190, s0, 0
	v_mbcnt_hi_u32_b32 v190, s1, v190
	v_add_u32_e32 v190, s98, v190
	v_cmp_gt_i32_e32 vcc, s19, v190
	s_bcnt1_i32_b64 s83, s[0:1]
	s_add_i32 s98, s98, s83
	s_and_b64 s[0:1], s[0:1], vcc
	s_or_b64 s[0:1], s[0:1], s[62:63]
	v_mbcnt_lo_u32_b32 v191, s0, 0
	v_mbcnt_hi_u32_b32 v191, s1, v191
	v_add_u32_e32 v191, s99, v191
	v_lshl_add_u32 v191, v191, 2, s79
	s_mov_b64 exec, s[0:1]
	ds_write2st64_b32 v191, v243, v217 offset1:8
	s_mov_b64 exec, s[4:5]
	s_bcnt1_i32_b64 s83, s[0:1]
	s_add_i32 s99, s99, s83
	v_cmp_eq_u32_e64 s[0:1], s56, v198
	s_nop 1
	v_mbcnt_lo_u32_b32 v190, s0, 0
	v_mbcnt_hi_u32_b32 v190, s1, v190
	v_add_u32_e32 v190, s98, v190
	v_cmp_gt_i32_e32 vcc, s19, v190
	s_bcnt1_i32_b64 s83, s[0:1]
	s_add_i32 s98, s98, s83
	s_and_b64 s[0:1], s[0:1], vcc
	s_or_b64 s[0:1], s[0:1], s[68:69]
	v_mbcnt_lo_u32_b32 v191, s0, 0
	v_mbcnt_hi_u32_b32 v191, s1, v191
	v_add_u32_e32 v191, s99, v191
	v_lshl_add_u32 v191, v191, 2, s79
	s_mov_b64 exec, s[0:1]
	ds_write2st64_b32 v191, v244, v218 offset1:8
	s_mov_b64 exec, s[4:5]
	s_bcnt1_i32_b64 s83, s[0:1]
	s_add_i32 s99, s99, s83
	v_cmp_eq_u32_e64 s[0:1], s56, v199
	s_nop 1
	v_mbcnt_lo_u32_b32 v190, s0, 0
	v_mbcnt_hi_u32_b32 v190, s1, v190
	v_add_u32_e32 v190, s98, v190
	v_cmp_gt_i32_e32 vcc, s19, v190
	s_bcnt1_i32_b64 s83, s[0:1]
	s_add_i32 s98, s98, s83
	s_and_b64 s[0:1], s[0:1], vcc
	s_or_b64 s[0:1], s[0:1], s[70:71]
	v_mbcnt_lo_u32_b32 v191, s0, 0
	v_mbcnt_hi_u32_b32 v191, s1, v191
	v_add_u32_e32 v191, s99, v191
	v_lshl_add_u32 v191, v191, 2, s79
	s_mov_b64 exec, s[0:1]
	ds_write2st64_b32 v191, v245, v219 offset1:8
	s_mov_b64 exec, s[4:5]
	s_bcnt1_i32_b64 s83, s[0:1]
	s_add_i32 s99, s99, s83
	v_cmp_eq_u32_e64 s[0:1], s56, v200
	s_nop 1
	v_mbcnt_lo_u32_b32 v190, s0, 0
	v_mbcnt_hi_u32_b32 v190, s1, v190
	v_add_u32_e32 v190, s98, v190
	v_cmp_gt_i32_e32 vcc, s19, v190
	s_bcnt1_i32_b64 s83, s[0:1]
	s_add_i32 s98, s98, s83
	s_and_b64 s[0:1], s[0:1], vcc
	s_or_b64 s[0:1], s[0:1], s[72:73]
	v_mbcnt_lo_u32_b32 v191, s0, 0
	v_mbcnt_hi_u32_b32 v191, s1, v191
	v_add_u32_e32 v191, s99, v191
	v_lshl_add_u32 v191, v191, 2, s79
	s_mov_b64 exec, s[0:1]
	ds_write2st64_b32 v191, v246, v220 offset1:8
	s_mov_b64 exec, s[4:5]
	s_bcnt1_i32_b64 s83, s[0:1]
	s_add_i32 s99, s99, s83
	v_cmp_eq_u32_e64 s[0:1], s56, v201
	s_nop 1
	v_mbcnt_lo_u32_b32 v190, s0, 0
	v_mbcnt_hi_u32_b32 v190, s1, v190
	v_add_u32_e32 v190, s98, v190
	v_cmp_gt_i32_e32 vcc, s19, v190
	s_bcnt1_i32_b64 s83, s[0:1]
	s_add_i32 s98, s98, s83
	s_and_b64 s[0:1], s[0:1], vcc
	s_or_b64 s[0:1], s[0:1], s[74:75]
	v_mbcnt_lo_u32_b32 v191, s0, 0
	v_mbcnt_hi_u32_b32 v191, s1, v191
	v_add_u32_e32 v191, s99, v191
	v_lshl_add_u32 v191, v191, 2, s79
	s_mov_b64 exec, s[0:1]
	ds_write2st64_b32 v191, v247, v221 offset1:8
	s_mov_b64 exec, s[4:5]
	s_bcnt1_i32_b64 s83, s[0:1]
	s_add_i32 s99, s99, s83
	s_ashr_i32 s0, s56, 31
	s_not_b32 s0, s0
	s_or_b32 s0, s0, 0x80000000
	s_xor_b32 s81, s56, s0
	s_cmp_eq_u32 s78, 0
	s_cbranch_scc1 .Lix_ret0
	s_cmp_eq_u32 s78, 1
	s_cbranch_scc1 .Lix_ret1
	s_cmp_eq_u32 s78, 2
	s_cbranch_scc1 .Lix_ret2
	s_cmp_eq_u32 s78, 3
	s_cbranch_scc1 .Lix_ret3
	s_cmp_eq_u32 s78, 4
	s_cbranch_scc1 .Lix_ret4
	s_cmp_eq_u32 s78, 5
	s_cbranch_scc1 .Lix_ret5
	s_cmp_eq_u32 s78, 6
	s_cbranch_scc1 .Lix_ret6
	s_cmp_eq_u32 s78, 7
	s_cbranch_scc1 .Lix_ret7
	s_cmp_eq_u32 s78, 8
	s_cbranch_scc1 .Lix_ret8
	s_cmp_eq_u32 s78, 9
	s_cbranch_scc1 .Lix_ret9
	s_cmp_eq_u32 s78, 10
	s_cbranch_scc1 .Lix_ret10
	s_cmp_eq_u32 s78, 11
	s_cbranch_scc1 .Lix_ret11
	s_endpgm
.Lix_exit:
	v_readlane_b32 s30, v254, 60
	v_readlane_b32 s31, v254, 61
	v_readlane_b32 s36, v254, 62
	v_readlane_b32 s37, v254, 63
	v_readlane_b32 s62, v254, 58
	v_readlane_b32 s63, v254, 59
	v_readlane_b32 s68, v250, 0
	v_readlane_b32 s69, v250, 1
	v_readlane_b32 s70, v250, 2
	v_readlane_b32 s71, v250, 3
	v_readlane_b32 s72, v250, 4
	v_readlane_b32 s73, v250, 5
	v_readlane_b32 s74, v250, 6
	v_readlane_b32 s75, v250, 7
	v_readlane_b32 s76, v250, 8
	v_readlane_b32 s77, v250, 9
	v_readlane_b32 s78, v250, 10
	v_readlane_b32 s79, v250, 11
	v_readlane_b32 s80, v250, 12
	v_readlane_b32 s81, v250, 13
	v_readlane_b32 s82, v250, 14
	v_readlane_b32 s83, v250, 15
	s_nop 3
	s_branch .LBB0_1003

; #define LAS __attribute__((address_space(3)))
; __global__ void __launch_bounds__(NTHREADS, 2) mega(Args a) {
;     extern __shared__ __attribute__((aligned(16))) unsigned char lds_raw[];
;     LAS unsigned char* lds = (LAS unsigned char*)lds_raw;
	.amdhsa_kernel _Z4mega4Args
		.amdhsa_group_segment_fixed_size 16384
		.amdhsa_private_segment_fixed_size 0
		.amdhsa_kernarg_size 424
		.amdhsa_user_sgpr_count 2
		.amdhsa_user_sgpr_dispatch_ptr 0
		.amdhsa_user_sgpr_queue_ptr 0
		.amdhsa_user_sgpr_kernarg_segment_ptr 1
		.amdhsa_user_sgpr_dispatch_id 0
		.amdhsa_user_sgpr_kernarg_preload_length 0
		.amdhsa_user_sgpr_kernarg_preload_offset 0
		.amdhsa_user_sgpr_private_segment_size 0
		.amdhsa_uses_dynamic_stack 0
		.amdhsa_enable_private_segment 0
		.amdhsa_system_sgpr_workgroup_id_x 1
		.amdhsa_system_sgpr_workgroup_id_y 0
		.amdhsa_system_sgpr_workgroup_id_z 0
		.amdhsa_system_sgpr_workgroup_info 0
		.amdhsa_system_vgpr_workitem_id 2
		.amdhsa_next_free_vgpr 255
		.amdhsa_next_free_sgpr 102
		.amdhsa_accum_offset 256
		.amdhsa_reserve_vcc 1
		.amdhsa_float_round_mode_32 0
		.amdhsa_float_round_mode_16_64 0
		.amdhsa_float_denorm_mode_32 3
		.amdhsa_float_denorm_mode_16_64 3
		.amdhsa_dx10_clamp 1
		.amdhsa_ieee_mode 1
		.amdhsa_fp16_overflow 0
		.amdhsa_tg_split 0
		.amdhsa_exception_fp_ieee_invalid_op 0
		.amdhsa_exception_fp_denorm_src 0
		.amdhsa_exception_fp_ieee_div_zero 0
		.amdhsa_exception_fp_ieee_overflow 0
		.amdhsa_exception_fp_ieee_underflow 0
		.amdhsa_exception_fp_ieee_inexact 0
		.amdhsa_exception_int_div_zero 0
	.end_amdhsa_kernel

; #define LAS __attribute__((address_space(3)))
; __global__ void __launch_bounds__(NTHREADS, 2) mega(Args a) {
;     extern __shared__ __attribute__((aligned(16))) unsigned char lds_raw[];
;     LAS unsigned char* lds = (LAS unsigned char*)lds_raw;
amdhsa.kernels:
  - .agpr_count:     0
    .args:
      - .offset:         0
        .size:           168
        .value_kind:     by_value
      - .offset:         168
        .size:           4
        .value_kind:     hidden_block_count_x
      - .offset:         172
        .size:           4
        .value_kind:     hidden_block_count_y
      - .offset:         176
        .size:           4
        .value_kind:     hidden_block_count_z
      - .offset:         180
        .size:           2
        .value_kind:     hidden_group_size_x
      - .offset:         182
        .size:           2
        .value_kind:     hidden_group_size_y
      - .offset:         184
        .size:           2
        .value_kind:     hidden_group_size_z
      - .offset:         186
        .size:           2
        .value_kind:     hidden_remainder_x
      - .offset:         188
        .size:           2
        .value_kind:     hidden_remainder_y
      - .offset:         190
        .size:           2
        .value_kind:     hidden_remainder_z
      - .offset:         208
        .size:           8
        .value_kind:     hidden_global_offset_x
      - .offset:         216
        .size:           8
        .value_kind:     hidden_global_offset_y
      - .offset:         224
        .size:           8
        .value_kind:     hidden_global_offset_z
      - .offset:         232
        .size:           2
        .value_kind:     hidden_grid_dims
      - .offset:         256
        .size:           8
        .value_kind:     hidden_multigrid_sync_arg
      - .offset:         288
        .size:           4
        .value_kind:     hidden_dynamic_lds_size
    .group_segment_fixed_size: 16384
    .kernarg_segment_align: 8
    .kernarg_segment_size: 424
    .language:       OpenCL C
    .language_version:
      - 2
      - 0
    .max_flat_workgroup_size: 512
    .name:           _Z4mega4Args
    .private_segment_fixed_size: 0
    .sgpr_count:     108
    .sgpr_spill_count: 302
    .symbol:         _Z4mega4Args.kd
    .uniform_work_group_size: 1
    .uses_dynamic_stack: false
    .vgpr_count:     255
    .vgpr_spill_count: 0
    .wavefront_size: 64
